# plus scan producer LDS-store block hand-written: 8 norm reductions stage-interleaved
# speedup vs baseline: 1.0285x; 1.0083x over previous
.LBB0_1237:
	s_bitcmp0_b32 s87, 0
	s_mov_b64 s[44:45], -1
	s_cselect_b64 s[42:43], -1, 0
	s_and_b64 vcc, exec, s[8:9]
	s_cbranch_vccz .LBB0_1243
	s_cmp_eq_u32 s40, 0x7e0000
	s_cbranch_scc1 .LBB0_1240
	s_and_b64 s[44:45], s[42:43], exec
	s_cselect_b32 s89, s66, 0
	s_and_b32 s44, s88, 0x7f8
	s_cmp_eq_u32 s44, 0
	s_cselect_b64 s[44:45], -1, 0
	s_waitcnt vmcnt(0)
	v_cndmask_b32_e64 v180, v72, 0, s[44:45]
	v_cndmask_b32_e64 v181, v73, 0, s[44:45]
	v_cndmask_b32_e64 v182, v74, 0, s[44:45]
	s_add_i32 s44, s59, s89
	v_lshl_add_u32 v7, v136, 2, s44
	v_sub_f32_e32 v172, v181, v41
	v_fma_f32 v140, v38, v172, v41
	v_mul_f32_e32 v148, v11, v140
	v_mul_f32_e32 v156, v148, v148
	v_sub_f32_e32 v172, v41, v45
	v_fma_f32 v141, v38, v172, v45
	v_mul_f32_e32 v149, v11, v141
	v_mul_f32_e32 v157, v149, v149
	v_sub_f32_e32 v172, v45, v49
	v_fma_f32 v142, v38, v172, v49
	v_mul_f32_e32 v150, v11, v142
	v_mul_f32_e32 v158, v150, v150
	v_sub_f32_e32 v172, v49, v53
	v_fma_f32 v143, v38, v172, v53
	v_mul_f32_e32 v151, v11, v143
	v_mul_f32_e32 v159, v151, v151
	v_sub_f32_e32 v172, v53, v57
	v_fma_f32 v144, v38, v172, v57
	v_mul_f32_e32 v152, v11, v144
	v_mul_f32_e32 v160, v152, v152
	v_sub_f32_e32 v172, v57, v61
	v_fma_f32 v145, v38, v172, v61
	v_mul_f32_e32 v153, v11, v145
	v_mul_f32_e32 v161, v153, v153
	v_sub_f32_e32 v172, v61, v65
	v_fma_f32 v146, v38, v172, v65
	v_mul_f32_e32 v154, v11, v146
	v_mul_f32_e32 v162, v154, v154
	v_sub_f32_e32 v172, v65, v69
	v_fma_f32 v147, v38, v172, v69
	v_mul_f32_e32 v155, v11, v147
	v_mul_f32_e32 v163, v155, v155
	v_add_f32_dpp v156, v156, v156 quad_perm:[1,0,3,2] row_mask:0xf bank_mask:0xf bound_ctrl:1
	v_add_f32_dpp v157, v157, v157 quad_perm:[1,0,3,2] row_mask:0xf bank_mask:0xf bound_ctrl:1
	v_add_f32_dpp v158, v158, v158 quad_perm:[1,0,3,2] row_mask:0xf bank_mask:0xf bound_ctrl:1
	v_add_f32_dpp v159, v159, v159 quad_perm:[1,0,3,2] row_mask:0xf bank_mask:0xf bound_ctrl:1
	v_add_f32_dpp v160, v160, v160 quad_perm:[1,0,3,2] row_mask:0xf bank_mask:0xf bound_ctrl:1
	v_add_f32_dpp v161, v161, v161 quad_perm:[1,0,3,2] row_mask:0xf bank_mask:0xf bound_ctrl:1
	v_add_f32_dpp v162, v162, v162 quad_perm:[1,0,3,2] row_mask:0xf bank_mask:0xf bound_ctrl:1
	v_add_f32_dpp v163, v163, v163 quad_perm:[1,0,3,2] row_mask:0xf bank_mask:0xf bound_ctrl:1
	v_add_f32_dpp v156, v156, v156 quad_perm:[2,3,0,1] row_mask:0xf bank_mask:0xf bound_ctrl:1
	v_add_f32_dpp v157, v157, v157 quad_perm:[2,3,0,1] row_mask:0xf bank_mask:0xf bound_ctrl:1
	v_add_f32_dpp v158, v158, v158 quad_perm:[2,3,0,1] row_mask:0xf bank_mask:0xf bound_ctrl:1
	v_add_f32_dpp v159, v159, v159 quad_perm:[2,3,0,1] row_mask:0xf bank_mask:0xf bound_ctrl:1
	v_add_f32_dpp v160, v160, v160 quad_perm:[2,3,0,1] row_mask:0xf bank_mask:0xf bound_ctrl:1
	v_add_f32_dpp v161, v161, v161 quad_perm:[2,3,0,1] row_mask:0xf bank_mask:0xf bound_ctrl:1
	v_add_f32_dpp v162, v162, v162 quad_perm:[2,3,0,1] row_mask:0xf bank_mask:0xf bound_ctrl:1
	v_add_f32_dpp v163, v163, v163 quad_perm:[2,3,0,1] row_mask:0xf bank_mask:0xf bound_ctrl:1
	v_add_f32_dpp v156, v156, v156 row_half_mirror row_mask:0xf bank_mask:0xf bound_ctrl:1
	v_add_f32_dpp v157, v157, v157 row_half_mirror row_mask:0xf bank_mask:0xf bound_ctrl:1
	v_add_f32_dpp v158, v158, v158 row_half_mirror row_mask:0xf bank_mask:0xf bound_ctrl:1
	v_add_f32_dpp v159, v159, v159 row_half_mirror row_mask:0xf bank_mask:0xf bound_ctrl:1
	v_add_f32_dpp v160, v160, v160 row_half_mirror row_mask:0xf bank_mask:0xf bound_ctrl:1
	v_add_f32_dpp v161, v161, v161 row_half_mirror row_mask:0xf bank_mask:0xf bound_ctrl:1
	v_add_f32_dpp v162, v162, v162 row_half_mirror row_mask:0xf bank_mask:0xf bound_ctrl:1
	v_add_f32_dpp v163, v163, v163 row_half_mirror row_mask:0xf bank_mask:0xf bound_ctrl:1
	v_add_f32_dpp v156, v156, v156 row_mirror row_mask:0xf bank_mask:0xf bound_ctrl:1
	v_add_f32_dpp v157, v157, v157 row_mirror row_mask:0xf bank_mask:0xf bound_ctrl:1
	v_add_f32_dpp v158, v158, v158 row_mirror row_mask:0xf bank_mask:0xf bound_ctrl:1
	v_add_f32_dpp v159, v159, v159 row_mirror row_mask:0xf bank_mask:0xf bound_ctrl:1
	v_add_f32_dpp v160, v160, v160 row_mirror row_mask:0xf bank_mask:0xf bound_ctrl:1
	v_add_f32_dpp v161, v161, v161 row_mirror row_mask:0xf bank_mask:0xf bound_ctrl:1
	v_add_f32_dpp v162, v162, v162 row_mirror row_mask:0xf bank_mask:0xf bound_ctrl:1
	v_add_f32_dpp v163, v163, v163 row_mirror row_mask:0xf bank_mask:0xf bound_ctrl:1
	v_mov_b32_e32 v164, v156
	v_mov_b32_e32 v165, v157
	v_mov_b32_e32 v166, v158
	v_mov_b32_e32 v167, v159
	v_mov_b32_e32 v168, v160
	v_mov_b32_e32 v169, v161
	v_mov_b32_e32 v170, v162
	v_mov_b32_e32 v171, v163
	v_permlane16_swap_b32 v156, v164
	v_permlane16_swap_b32 v157, v165
	v_permlane16_swap_b32 v158, v166
	v_permlane16_swap_b32 v159, v167
	v_permlane16_swap_b32 v160, v168
	v_permlane16_swap_b32 v161, v169
	v_permlane16_swap_b32 v162, v170
	v_permlane16_swap_b32 v163, v171
	v_add_f32_e32 v156, v156, v164
	v_add_f32_e32 v157, v157, v165
	v_add_f32_e32 v158, v158, v166
	v_add_f32_e32 v159, v159, v167
	v_add_f32_e32 v160, v160, v168
	v_add_f32_e32 v161, v161, v169
	v_add_f32_e32 v162, v162, v170
	v_add_f32_e32 v163, v163, v171
	v_mov_b32_e32 v164, v156
	v_mov_b32_e32 v165, v157
	v_mov_b32_e32 v166, v158
	v_mov_b32_e32 v167, v159
	v_mov_b32_e32 v168, v160
	v_mov_b32_e32 v169, v161
	v_mov_b32_e32 v170, v162
	v_mov_b32_e32 v171, v163
	v_permlane32_swap_b32 v156, v164
	v_permlane32_swap_b32 v157, v165
	v_permlane32_swap_b32 v158, v166
	v_permlane32_swap_b32 v159, v167
	v_permlane32_swap_b32 v160, v168
	v_permlane32_swap_b32 v161, v169
	v_permlane32_swap_b32 v162, v170
	v_permlane32_swap_b32 v163, v171
	v_add_f32_e32 v156, v156, v164
	v_add_f32_e32 v157, v157, v165
	v_add_f32_e32 v158, v158, v166
	v_add_f32_e32 v159, v159, v167
	v_add_f32_e32 v160, v160, v168
	v_add_f32_e32 v161, v161, v169
	v_add_f32_e32 v162, v162, v170
	v_add_f32_e32 v163, v163, v171
	v_max_f32_e32 v156, 0x179abe15, v156
	v_max_f32_e32 v157, 0x179abe15, v157
	v_max_f32_e32 v158, 0x179abe15, v158
	v_max_f32_e32 v159, 0x179abe15, v159
	v_max_f32_e32 v160, 0x179abe15, v160
	v_max_f32_e32 v161, 0x179abe15, v161
	v_max_f32_e32 v162, 0x179abe15, v162
	v_max_f32_e32 v163, 0x179abe15, v163
	v_rsq_f32_e32 v156, v156
	v_rsq_f32_e32 v157, v157
	v_rsq_f32_e32 v158, v158
	v_rsq_f32_e32 v159, v159
	v_rsq_f32_e32 v160, v160
	v_rsq_f32_e32 v161, v161
	v_rsq_f32_e32 v162, v162
	v_rsq_f32_e32 v163, v163
	v_mul_f32_e32 v148, v148, v156
	v_mul_f32_e32 v149, v149, v157
	v_mul_f32_e32 v150, v150, v158
	v_mul_f32_e32 v151, v151, v159
	v_mul_f32_e32 v152, v152, v160
	v_mul_f32_e32 v153, v153, v161
	v_mul_f32_e32 v154, v154, v162
	v_mul_f32_e32 v155, v155, v163
	v_sub_f32_e32 v172, v180, v40
	v_sub_f32_e32 v173, v182, v42
	v_add_f32_e32 v174, -1.0, v13
	v_fma_f32 v172, v37, v172, v40
	v_fma_f32 v173, v39, v173, v42
	v_fma_f32 v174, v36, v174, 1.0
	v_mul_f32_e32 v175, v13, v148
	v_mul_f32_e32 v174, v140, v174
	ds_write2st64_b32 v7, v173, v43 offset0:64 offset1:96
	ds_write2st64_b32 v7, v148, v175 offset0:128 offset1:160
	ds_write2st64_b32 v7, v172, v174 offset0:0 offset1:32
	v_sub_f32_e32 v172, v40, v44
	v_sub_f32_e32 v173, v42, v46
	v_add_f32_e32 v174, -1.0, v12
	v_fma_f32 v172, v37, v172, v44
	v_fma_f32 v173, v39, v173, v46
	v_fma_f32 v174, v36, v174, 1.0
	v_mul_f32_e32 v175, v12, v149
	v_mul_f32_e32 v174, v141, v174
	ds_write2st64_b32 v7, v173, v47 offset0:65 offset1:97
	ds_write2st64_b32 v7, v149, v175 offset0:129 offset1:161
	ds_write2st64_b32 v7, v172, v174 offset0:1 offset1:33
	v_sub_f32_e32 v172, v44, v48
	v_sub_f32_e32 v173, v46, v50
	v_add_f32_e32 v174, -1.0, v15
	v_fma_f32 v172, v37, v172, v48
	v_fma_f32 v173, v39, v173, v50
	v_fma_f32 v174, v36, v174, 1.0
	v_mul_f32_e32 v175, v15, v150
	v_mul_f32_e32 v174, v142, v174
	ds_write2st64_b32 v7, v173, v51 offset0:66 offset1:98
	ds_write2st64_b32 v7, v150, v175 offset0:130 offset1:162
	ds_write2st64_b32 v7, v172, v174 offset0:2 offset1:34
	v_sub_f32_e32 v172, v48, v52
	v_sub_f32_e32 v173, v50, v54
	v_add_f32_e32 v174, -1.0, v14
	v_fma_f32 v172, v37, v172, v52
	v_fma_f32 v173, v39, v173, v54
	v_fma_f32 v174, v36, v174, 1.0
	v_mul_f32_e32 v175, v14, v151
	v_mul_f32_e32 v174, v143, v174
	ds_write2st64_b32 v7, v173, v55 offset0:67 offset1:99
	ds_write2st64_b32 v7, v151, v175 offset0:131 offset1:163
	ds_write2st64_b32 v7, v172, v174 offset0:3 offset1:35
	v_sub_f32_e32 v172, v52, v56
	v_sub_f32_e32 v173, v54, v58
	v_add_f32_e32 v174, -1.0, v17
	v_fma_f32 v172, v37, v172, v56
	v_fma_f32 v173, v39, v173, v58
	v_fma_f32 v174, v36, v174, 1.0
	v_mul_f32_e32 v175, v17, v152
	v_mul_f32_e32 v174, v144, v174
	ds_write2st64_b32 v7, v173, v59 offset0:68 offset1:100
	ds_write2st64_b32 v7, v152, v175 offset0:132 offset1:164
	ds_write2st64_b32 v7, v172, v174 offset0:4 offset1:36
	v_sub_f32_e32 v172, v56, v60
	v_sub_f32_e32 v173, v58, v62
	v_add_f32_e32 v174, -1.0, v16
	v_fma_f32 v172, v37, v172, v60
	v_fma_f32 v173, v39, v173, v62
	v_fma_f32 v174, v36, v174, 1.0
	v_mul_f32_e32 v175, v16, v153
	v_mul_f32_e32 v174, v145, v174
	ds_write2st64_b32 v7, v173, v63 offset0:69 offset1:101
	ds_write2st64_b32 v7, v153, v175 offset0:133 offset1:165
	ds_write2st64_b32 v7, v172, v174 offset0:5 offset1:37
	v_sub_f32_e32 v172, v60, v64
	v_sub_f32_e32 v173, v62, v66
	v_add_f32_e32 v174, -1.0, v19
	v_fma_f32 v172, v37, v172, v64
	v_fma_f32 v173, v39, v173, v66
	v_fma_f32 v174, v36, v174, 1.0
	v_mul_f32_e32 v175, v19, v154
	v_mul_f32_e32 v174, v146, v174
	ds_write2st64_b32 v7, v173, v67 offset0:70 offset1:102
	ds_write2st64_b32 v7, v154, v175 offset0:134 offset1:166
	ds_write2st64_b32 v7, v172, v174 offset0:6 offset1:38
	v_sub_f32_e32 v172, v64, v68
	v_sub_f32_e32 v173, v66, v70
	v_add_f32_e32 v174, -1.0, v18
	v_fma_f32 v172, v37, v172, v68
	v_fma_f32 v173, v39, v173, v70
	v_fma_f32 v174, v36, v174, 1.0
	v_mul_f32_e32 v175, v18, v155
	v_mul_f32_e32 v174, v147, v174
	ds_write2st64_b32 v7, v173, v71 offset0:71 offset1:103
	ds_write2st64_b32 v7, v155, v175 offset0:135 offset1:167
	ds_write2st64_b32 v7, v172, v174 offset0:7 offset1:39
